# P8 epilogue: per-wave LDS lane transpose so each f32 store instruction writes 8 full 128-B lines; P7: quad-coalesced stores
# speedup vs baseline: 1.0229x; 1.0093x over previous
; __device__ __forceinline__ u32x4 pack8(const f32x4& a, const f32x4& b) { u32x4 w; w.x = cvt_pk_bf16(a[0], a[1]); w.y = cvt_pk_bf16(a[2], a[3]); w.z = cvt_pk_bf16(b[0], b[1]); w.w = cvt_pk_bf16(b[2], b[3]); return w; }
; __device__ __forceinline__ float frsq(float x) { return __builtin_amdgcn_rsqf(x); }
;     __device__ __forceinline__ void operator()(Acc& acc, const Unit& u, int wr, int wc, int fr, int fq) const {
;         asm volatile("" : "+v"(fr), "+v"(fq));
;         const int row0 = u.pm * BM + wr * 64 + fr, col0 = u.pn * BM + wc * 32 + 8 * fq;
;         float ssv[2][4];
;         if (ACT == 0) {
; #pragma unroll
;             for (int ai = 0; ai < 2; ++ai)
; #pragma unroll
;                 for (int m = 0; m < 4; ++m) ssv[ai][m] = sumsq[row0 + ai * HALF + m * 16];
;             __builtin_amdgcn_sched_barrier(0);
;         }
; #pragma unroll
;         for (int ai = 0; ai < 2; ++ai)
; #pragma unroll
;             for (int m = 0; m < 4; ++m) { const int row = row0 + ai * HALF + m * 16; const float rstd = (ACT == 0) ? frsq(ssv[ai][m] * (1.0f / D) + EPS) : 1.0f;
; #pragma unroll
;                 for (int bj = 0; bj < 2; ++bj) { f32x4 a = acc[ai][bj][m][0] * rstd, b = acc[ai][bj][m][1] * rstd;
;                     if (ACT == 1) {
; #pragma unroll
;                         for (int i = 0; i < 4; ++i) { const float x = fmaxf(a[i], 0.f), y = fmaxf(b[i], 0.f); a[i] = x * x; b[i] = y * y; } }
;                     *(u32x4*)(O + (size_t)row * ldc + col0 + bj * HALF) = pack8(a, b); }
.LBB0_1091:
	v_lshrrev_b32_e32 v222, 6, v228
	v_mul_u32_u24_e32 v222, 0x500, v222
	v_add_u32_e32 v222, 0x20000, v222
	v_mul_u32_u24_e32 v223, 0x50, v140
	v_lshl_add_u32 v223, v141, 4, v223
	v_add_u32_e32 v220, v222, v223
	v_bfe_u32 v223, v228, 2, 4
	v_mul_u32_u24_e32 v223, 0x50, v223
	v_and_b32_e32 v221, 3, v228
	v_lshl_add_u32 v223, v221, 4, v223
	v_add_u32_e32 v221, v222, v223
	v_bfe_u32 v146, v228, 2, 4
	v_and_b32_e32 v147, 3, v228
	s_lshl_b32 s6, s6, 8
	s_add_i32 s6, s6, s58
	v_add_u32_e32 v146, s6, v146
	s_lshl_b32 s6, s71, 8
	v_max_f32_e32 v122, 0, v122
	s_or_b32 s6, s6, s59
	v_max_f32_e32 v124, 0, v124
	v_max_f32_e32 v120, 0, v120
	v_max_f32_e32 v121, 0, v121
	v_mul_f32_e32 v150, v122, v122
	v_max_f32_e32 v122, v127, v127
	v_lshl_add_u32 v148, v147, 3, s6
	v_ashrrev_i32_e32 v147, 31, v146
	v_mul_f32_e32 v124, v124, v124
	v_mul_f32_e32 v120, v120, v120
	v_max_f32_e32 v125, 0, v125
	v_mul_f32_e32 v121, v121, v121
	v_max_f32_e32 v126, 0, v126
	v_max_f32_e32 v122, 0, v122
	v_max_f32_e32 v123, 0, v123
	v_mul_f32_e32 v125, v125, v125
	v_mul_f32_e32 v126, v126, v126
	v_mul_f32_e32 v127, v122, v122
	v_mul_f32_e32 v151, v123, v123
	v_cvt_pk_bf16_f32 v122, v124, v125
	v_cvt_pk_bf16_f32 v123, v126, v127
	v_cvt_pk_bf16_f32 v124, v120, v121
	v_lshlrev_b64 v[120:121], 13, v[146:147]
	v_ashrrev_i32_e32 v149, 31, v148
	v_lshl_add_u64 v[120:121], s[12:13], 0, v[120:121]
	v_lshl_add_u64 v[120:121], v[148:149], 1, v[120:121]
	v_max_f32_e32 v112, 0, v112
	v_cvt_pk_bf16_f32 v125, v150, v151
	ds_write_b128 v220, v[122:125]
	ds_read_b128 v[232:235], v221
	v_mov_b64_e32 v[240:241], v[120:121]
	v_max_f32_e32 v113, 0, v113
	v_max_f32_e32 v114, 0, v114
	v_mul_f32_e32 v122, v112, v112
	v_max_f32_e32 v112, v117, v117
	v_max_f32_e32 v112, 0, v112
	v_mul_f32_e32 v117, v113, v113
	v_max_f32_e32 v113, v118, v118
	v_mul_f32_e32 v118, v114, v114
	v_max_f32_e32 v114, v119, v119
	v_max_f32_e32 v116, 0, v116
	v_mul_f32_e32 v112, v112, v112
	v_max_f32_e32 v113, 0, v113
	v_max_f32_e32 v114, 0, v114
	v_max_f32_e32 v115, 0, v115
	v_mul_f32_e32 v116, v116, v116
	v_mul_f32_e32 v113, v113, v113
	v_mul_f32_e32 v114, v114, v114
	v_mul_f32_e32 v115, v115, v115
	v_cvt_pk_bf16_f32 v112, v116, v112
	v_max_f32_e32 v104, 0, v104
	v_max_f32_e32 v105, 0, v105
	v_max_f32_e32 v106, 0, v106
	v_cvt_pk_bf16_f32 v113, v113, v114
	v_cvt_pk_bf16_f32 v114, v122, v117
	v_cvt_pk_bf16_f32 v115, v118, v115
	ds_write_b128 v220, v[112:115]
	ds_read_b128 v[236:239], v221
	v_mov_b64_e32 v[242:243], v[120:121]
	s_waitcnt lgkmcnt(2)
	global_store_dwordx4 v[240:241], v[232:235], off
	s_nop 1
	v_mul_f32_e32 v112, v104, v104
	v_max_f32_e32 v104, v109, v109
	v_mul_f32_e32 v109, v105, v105
	v_max_f32_e32 v105, v110, v110
	v_mul_f32_e32 v110, v106, v106
	v_max_f32_e32 v106, v111, v111
	v_max_f32_e32 v104, 0, v104
	v_max_f32_e32 v105, 0, v105
	v_max_f32_e32 v106, 0, v106
	v_max_f32_e32 v107, 0, v107
	v_max_f32_e32 v108, 0, v108
	v_mul_f32_e32 v104, v104, v104
	v_mul_f32_e32 v105, v105, v105
	v_mul_f32_e32 v106, v106, v106
	v_mul_f32_e32 v107, v107, v107
	v_mul_f32_e32 v108, v108, v108
	v_cvt_pk_bf16_f32 v104, v108, v104
	v_cvt_pk_bf16_f32 v105, v105, v106
	v_cvt_pk_bf16_f32 v106, v112, v109
	v_cvt_pk_bf16_f32 v107, v110, v107
	v_add_co_u32_e32 v110, vcc, s64, v120
	s_nop 0
	v_addc_co_u32_e32 v111, vcc, 0, v121, vcc
	v_max_f32_e32 v96, 0, v96
	ds_write_b128 v220, v[104:107]
	ds_read_b128 v[232:235], v221
	v_mov_b64_e32 v[240:241], v[110:111]
	s_waitcnt lgkmcnt(2)
	global_store_dwordx4 v[242:243], v[236:239], off offset:256
	v_max_f32_e32 v97, 0, v97
	v_max_f32_e32 v98, 0, v98
	v_mul_f32_e32 v104, v96, v96
	v_max_f32_e32 v96, v101, v101
	v_max_f32_e32 v96, 0, v96
	v_mul_f32_e32 v101, v97, v97
	v_max_f32_e32 v97, v102, v102
	v_mul_f32_e32 v102, v98, v98
	v_max_f32_e32 v98, v103, v103
	v_max_f32_e32 v100, 0, v100
	v_mul_f32_e32 v96, v96, v96
	v_max_f32_e32 v97, 0, v97
	v_max_f32_e32 v98, 0, v98
	v_max_f32_e32 v99, 0, v99
	v_lshl_add_u64 v[108:109], v[120:121], 0, s[18:19]
	v_mul_f32_e32 v100, v100, v100
	v_mul_f32_e32 v97, v97, v97
	v_mul_f32_e32 v98, v98, v98
	v_mul_f32_e32 v99, v99, v99
	v_cvt_pk_bf16_f32 v96, v100, v96
	v_max_f32_e32 v88, 0, v88
	v_max_f32_e32 v89, 0, v89
	v_max_f32_e32 v90, 0, v90
	v_cvt_pk_bf16_f32 v97, v97, v98
	v_cvt_pk_bf16_f32 v98, v104, v101
	v_cvt_pk_bf16_f32 v99, v102, v99
	ds_write_b128 v220, v[96:99]
	ds_read_b128 v[236:239], v221
	v_mov_b64_e32 v[242:243], v[108:109]
	s_waitcnt lgkmcnt(2)
	global_store_dwordx4 v[240:241], v[232:235], off
	s_nop 1
	v_mul_f32_e32 v96, v88, v88
	v_max_f32_e32 v88, v93, v93
	v_mul_f32_e32 v93, v89, v89
	v_max_f32_e32 v89, v94, v94
	v_mul_f32_e32 v94, v90, v90
	v_max_f32_e32 v90, v95, v95
	v_max_f32_e32 v88, 0, v88
	v_max_f32_e32 v89, 0, v89
	v_max_f32_e32 v90, 0, v90
	v_max_f32_e32 v91, 0, v91
	v_max_f32_e32 v92, 0, v92
	v_mul_f32_e32 v88, v88, v88
	v_mul_f32_e32 v89, v89, v89
	v_mul_f32_e32 v90, v90, v90
	v_mul_f32_e32 v91, v91, v91
	v_mul_f32_e32 v92, v92, v92
	v_cvt_pk_bf16_f32 v88, v92, v88
	v_cvt_pk_bf16_f32 v89, v89, v90
	v_cvt_pk_bf16_f32 v90, v96, v93
	v_cvt_pk_bf16_f32 v91, v94, v91
	v_add_co_u32_e32 v94, vcc, s65, v120
	s_nop 0
	v_addc_co_u32_e32 v95, vcc, 0, v121, vcc
	v_max_f32_e32 v80, 0, v80
	ds_write_b128 v220, v[88:91]
	ds_read_b128 v[232:235], v221
	v_mov_b64_e32 v[240:241], v[94:95]
	s_waitcnt lgkmcnt(2)
; __device__ __forceinline__ u32x4 pack8(const f32x4& a, const f32x4& b) { u32x4 w; w.x = cvt_pk_bf16(a[0], a[1]); w.y = cvt_pk_bf16(a[2], a[3]); w.z = cvt_pk_bf16(b[0], b[1]); w.w = cvt_pk_bf16(b[2], b[3]); return w; }
; __device__ __forceinline__ float frsq(float x) { return __builtin_amdgcn_rsqf(x); }
;     __device__ __forceinline__ void operator()(Acc& acc, const Unit& u, int wr, int wc, int fr, int fq) const {
;     ...
; #pragma unroll
;         for (int ai = 0; ai < 2; ++ai)
; #pragma unroll
;             for (int m = 0; m < 4; ++m) { const int row = row0 + ai * HALF + m * 16; const float rstd = (ACT == 0) ? frsq(ssv[ai][m] * (1.0f / D) + EPS) : 1.0f;
; #pragma unroll
;                 for (int bj = 0; bj < 2; ++bj) { f32x4 a = acc[ai][bj][m][0] * rstd, b = acc[ai][bj][m][1] * rstd;
;                     if (ACT == 1) {
; #pragma unroll
;                         for (int i = 0; i < 4; ++i) { const float x = fmaxf(a[i], 0.f), y = fmaxf(b[i], 0.f); a[i] = x * x; b[i] = y * y; } }
;                     *(u32x4*)(O + (size_t)row * ldc + col0 + bj * HALF) = pack8(a, b); }
	global_store_dwordx4 v[242:243], v[236:239], off offset:256
	v_max_f32_e32 v81, 0, v81
	v_max_f32_e32 v82, 0, v82
	v_mul_f32_e32 v88, v80, v80
	v_max_f32_e32 v80, v85, v85
	v_max_f32_e32 v80, 0, v80
	v_mul_f32_e32 v85, v81, v81
	v_max_f32_e32 v81, v86, v86
	v_mul_f32_e32 v86, v82, v82
	v_max_f32_e32 v82, v87, v87
	v_max_f32_e32 v84, 0, v84
	v_mul_f32_e32 v80, v80, v80
	v_max_f32_e32 v81, 0, v81
	v_max_f32_e32 v82, 0, v82
	v_max_f32_e32 v83, 0, v83
	v_lshl_add_u64 v[92:93], v[120:121], 0, s[8:9]
	v_mul_f32_e32 v84, v84, v84
	v_mul_f32_e32 v81, v81, v81
	v_mul_f32_e32 v82, v82, v82
	v_mul_f32_e32 v83, v83, v83
	v_cvt_pk_bf16_f32 v80, v84, v80
	v_max_f32_e32 v72, 0, v72
	v_max_f32_e32 v73, 0, v73
	v_max_f32_e32 v74, 0, v74
	v_cvt_pk_bf16_f32 v81, v81, v82
	v_cvt_pk_bf16_f32 v82, v88, v85
	v_cvt_pk_bf16_f32 v83, v86, v83
	ds_write_b128 v220, v[80:83]
	ds_read_b128 v[236:239], v221
	v_mov_b64_e32 v[242:243], v[92:93]
	s_waitcnt lgkmcnt(2)
	global_store_dwordx4 v[240:241], v[232:235], off
	s_nop 1
	v_mul_f32_e32 v80, v72, v72
	v_max_f32_e32 v72, v77, v77
	v_mul_f32_e32 v77, v73, v73
	v_max_f32_e32 v73, v78, v78
	v_mul_f32_e32 v78, v74, v74
	v_max_f32_e32 v74, v79, v79
	v_max_f32_e32 v72, 0, v72
	v_max_f32_e32 v73, 0, v73
	v_max_f32_e32 v74, 0, v74
	v_max_f32_e32 v75, 0, v75
	v_max_f32_e32 v76, 0, v76
	v_mul_f32_e32 v72, v72, v72
	v_mul_f32_e32 v73, v73, v73
	v_mul_f32_e32 v74, v74, v74
	v_mul_f32_e32 v75, v75, v75
	v_mul_f32_e32 v76, v76, v76
	v_cvt_pk_bf16_f32 v72, v76, v72
	v_cvt_pk_bf16_f32 v73, v73, v74
	v_cvt_pk_bf16_f32 v74, v80, v77
	v_cvt_pk_bf16_f32 v75, v78, v75
	v_add_co_u32_e32 v78, vcc, s66, v120
	s_nop 0
	v_addc_co_u32_e32 v79, vcc, 0, v121, vcc
	v_max_f32_e32 v64, 0, v64
	ds_write_b128 v220, v[72:75]
	ds_read_b128 v[232:235], v221
	v_mov_b64_e32 v[240:241], v[78:79]
	s_waitcnt lgkmcnt(2)
	global_store_dwordx4 v[242:243], v[236:239], off offset:256
	v_max_f32_e32 v65, 0, v65
	v_max_f32_e32 v66, 0, v66
	v_mul_f32_e32 v72, v64, v64
	v_max_f32_e32 v64, v69, v69
	v_max_f32_e32 v64, 0, v64
	v_mul_f32_e32 v69, v65, v65
	v_max_f32_e32 v65, v70, v70
	v_mul_f32_e32 v70, v66, v66
	v_max_f32_e32 v66, v71, v71
	v_max_f32_e32 v68, 0, v68
	v_mul_f32_e32 v64, v64, v64
	v_max_f32_e32 v65, 0, v65
	v_max_f32_e32 v66, 0, v66
	v_max_f32_e32 v67, 0, v67
	v_lshl_add_u64 v[76:77], v[120:121], 0, s[20:21]
	v_mul_f32_e32 v68, v68, v68
	v_mul_f32_e32 v65, v65, v65
	v_mul_f32_e32 v66, v66, v66
	v_mul_f32_e32 v67, v67, v67
	v_cvt_pk_bf16_f32 v64, v68, v64
	v_max_f32_e32 v56, 0, v56
	v_max_f32_e32 v57, 0, v57
	v_max_f32_e32 v58, 0, v58
	v_cvt_pk_bf16_f32 v65, v65, v66
	v_cvt_pk_bf16_f32 v66, v72, v69
	v_cvt_pk_bf16_f32 v67, v70, v67
	ds_write_b128 v220, v[64:67]
	ds_read_b128 v[236:239], v221
	v_mov_b64_e32 v[242:243], v[76:77]
	s_waitcnt lgkmcnt(2)
	global_store_dwordx4 v[240:241], v[232:235], off
	s_nop 1
	v_mul_f32_e32 v64, v56, v56
	v_max_f32_e32 v56, v61, v61
	v_mul_f32_e32 v61, v57, v57
	v_max_f32_e32 v57, v62, v62
	v_mul_f32_e32 v62, v58, v58
	v_max_f32_e32 v58, v63, v63
	v_max_f32_e32 v56, 0, v56
	v_max_f32_e32 v57, 0, v57
	v_max_f32_e32 v58, 0, v58
	v_max_f32_e32 v59, 0, v59
	v_max_f32_e32 v60, 0, v60
	v_mul_f32_e32 v56, v56, v56
	v_mul_f32_e32 v57, v57, v57
	v_mul_f32_e32 v58, v58, v58
	v_mul_f32_e32 v59, v59, v59
	v_mul_f32_e32 v60, v60, v60
	v_cvt_pk_bf16_f32 v56, v60, v56
	v_cvt_pk_bf16_f32 v57, v57, v58
	v_cvt_pk_bf16_f32 v58, v64, v61
	v_cvt_pk_bf16_f32 v59, v62, v59
	v_add_co_u32_e32 v62, vcc, s67, v120
	s_nop 0
	v_addc_co_u32_e32 v63, vcc, 0, v121, vcc
	v_max_f32_e32 v48, 0, v48
	ds_write_b128 v220, v[56:59]
	ds_read_b128 v[232:235], v221
	v_mov_b64_e32 v[240:241], v[62:63]
	s_waitcnt lgkmcnt(2)
	global_store_dwordx4 v[242:243], v[236:239], off offset:256
	v_max_f32_e32 v49, 0, v49
	v_max_f32_e32 v50, 0, v50
	v_mul_f32_e32 v56, v48, v48
	v_max_f32_e32 v48, v53, v53
	v_max_f32_e32 v48, 0, v48
	v_mul_f32_e32 v53, v49, v49
	v_max_f32_e32 v49, v54, v54
	v_mul_f32_e32 v54, v50, v50
	v_max_f32_e32 v50, v55, v55
	v_max_f32_e32 v52, 0, v52
	v_mul_f32_e32 v48, v48, v48
	v_max_f32_e32 v49, 0, v49
	v_max_f32_e32 v50, 0, v50
	v_max_f32_e32 v51, 0, v51
	v_lshl_add_u64 v[60:61], v[120:121], 0, s[22:23]
	v_mul_f32_e32 v52, v52, v52
	v_mul_f32_e32 v49, v49, v49
	v_mul_f32_e32 v50, v50, v50
	v_mul_f32_e32 v51, v51, v51
	v_cvt_pk_bf16_f32 v48, v52, v48
	v_max_f32_e32 v40, 0, v40
	v_max_f32_e32 v41, 0, v41
	v_max_f32_e32 v42, 0, v42
	v_cvt_pk_bf16_f32 v49, v49, v50
	v_cvt_pk_bf16_f32 v50, v56, v53
	v_cvt_pk_bf16_f32 v51, v54, v51
	ds_write_b128 v220, v[48:51]
	ds_read_b128 v[236:239], v221
	v_mov_b64_e32 v[242:243], v[60:61]
	s_waitcnt lgkmcnt(2)
	global_store_dwordx4 v[240:241], v[232:235], off
	s_nop 1
	v_mul_f32_e32 v48, v40, v40
	v_max_f32_e32 v40, v45, v45
	v_mul_f32_e32 v45, v41, v41
	v_max_f32_e32 v41, v46, v46
	v_mul_f32_e32 v46, v42, v42
	v_max_f32_e32 v42, v47, v47
	v_max_f32_e32 v40, 0, v40
	v_max_f32_e32 v41, 0, v41
	v_max_f32_e32 v42, 0, v42
	v_max_f32_e32 v43, 0, v43
	v_max_f32_e32 v44, 0, v44
	v_mul_f32_e32 v40, v40, v40
	v_mul_f32_e32 v41, v41, v41
	v_mul_f32_e32 v42, v42, v42
	v_mul_f32_e32 v43, v43, v43
	v_mul_f32_e32 v44, v44, v44
	v_cvt_pk_bf16_f32 v40, v44, v40
	v_cvt_pk_bf16_f32 v41, v41, v42
	v_cvt_pk_bf16_f32 v42, v48, v45
	v_cvt_pk_bf16_f32 v43, v46, v43
	v_add_co_u32_e32 v46, vcc, s68, v120
	s_nop 0
	v_addc_co_u32_e32 v47, vcc, 0, v121, vcc
	v_max_f32_e32 v32, 0, v32
	ds_write_b128 v220, v[40:43]
	ds_read_b128 v[232:235], v221
	v_mov_b64_e32 v[240:241], v[46:47]
	s_waitcnt lgkmcnt(2)
; __device__ __forceinline__ u32x4 pack8(const f32x4& a, const f32x4& b) { u32x4 w; w.x = cvt_pk_bf16(a[0], a[1]); w.y = cvt_pk_bf16(a[2], a[3]); w.z = cvt_pk_bf16(b[0], b[1]); w.w = cvt_pk_bf16(b[2], b[3]); return w; }
; __device__ __forceinline__ float frsq(float x) { return __builtin_amdgcn_rsqf(x); }
;     __device__ __forceinline__ void operator()(Acc& acc, const Unit& u, int wr, int wc, int fr, int fq) const {
;     ...
; #pragma unroll
;         for (int ai = 0; ai < 2; ++ai)
; #pragma unroll
;             for (int m = 0; m < 4; ++m) { const int row = row0 + ai * HALF + m * 16; const float rstd = (ACT == 0) ? frsq(ssv[ai][m] * (1.0f / D) + EPS) : 1.0f;
; #pragma unroll
;                 for (int bj = 0; bj < 2; ++bj) { f32x4 a = acc[ai][bj][m][0] * rstd, b = acc[ai][bj][m][1] * rstd;
;                     if (ACT == 1) {
; #pragma unroll
;                         for (int i = 0; i < 4; ++i) { const float x = fmaxf(a[i], 0.f), y = fmaxf(b[i], 0.f); a[i] = x * x; b[i] = y * y; } }
;                     *(u32x4*)(O + (size_t)row * ldc + col0 + bj * HALF) = pack8(a, b); }
	global_store_dwordx4 v[242:243], v[236:239], off offset:256
	v_max_f32_e32 v33, 0, v33
	v_max_f32_e32 v34, 0, v34
	v_mul_f32_e32 v40, v32, v32
	v_max_f32_e32 v32, v37, v37
	v_max_f32_e32 v32, 0, v32
	v_mul_f32_e32 v37, v33, v33
	v_max_f32_e32 v33, v38, v38
	v_mul_f32_e32 v38, v34, v34
	v_max_f32_e32 v34, v39, v39
	v_max_f32_e32 v36, 0, v36
	v_mul_f32_e32 v32, v32, v32
	v_max_f32_e32 v33, 0, v33
	v_max_f32_e32 v34, 0, v34
	v_max_f32_e32 v35, 0, v35
	v_lshl_add_u64 v[44:45], v[120:121], 0, s[24:25]
	v_mul_f32_e32 v36, v36, v36
	v_mul_f32_e32 v33, v33, v33
	v_mul_f32_e32 v34, v34, v34
	v_mul_f32_e32 v35, v35, v35
	v_cvt_pk_bf16_f32 v32, v36, v32
	v_max_f32_e32 v24, 0, v24
	v_max_f32_e32 v25, 0, v25
	v_max_f32_e32 v26, 0, v26
	v_cvt_pk_bf16_f32 v33, v33, v34
	v_cvt_pk_bf16_f32 v34, v40, v37
	v_cvt_pk_bf16_f32 v35, v38, v35
	ds_write_b128 v220, v[32:35]
	ds_read_b128 v[236:239], v221
	v_mov_b64_e32 v[242:243], v[44:45]
	s_waitcnt lgkmcnt(2)
	global_store_dwordx4 v[240:241], v[232:235], off
	s_nop 1
	v_mul_f32_e32 v32, v24, v24
	v_max_f32_e32 v24, v29, v29
	v_mul_f32_e32 v29, v25, v25
	v_max_f32_e32 v25, v30, v30
	v_mul_f32_e32 v30, v26, v26
	v_max_f32_e32 v26, v31, v31
	v_max_f32_e32 v24, 0, v24
	v_max_f32_e32 v25, 0, v25
	v_max_f32_e32 v26, 0, v26
	v_max_f32_e32 v27, 0, v27
	v_max_f32_e32 v28, 0, v28
	v_mul_f32_e32 v24, v24, v24
	v_mul_f32_e32 v25, v25, v25
	v_mul_f32_e32 v26, v26, v26
	v_mul_f32_e32 v27, v27, v27
	v_mul_f32_e32 v28, v28, v28
	v_cvt_pk_bf16_f32 v24, v28, v24
	v_cvt_pk_bf16_f32 v25, v25, v26
	v_cvt_pk_bf16_f32 v26, v32, v29
	v_cvt_pk_bf16_f32 v27, v30, v27
	v_add_co_u32_e32 v30, vcc, s69, v120
	s_nop 0
	v_addc_co_u32_e32 v31, vcc, 0, v121, vcc
	v_max_f32_e32 v16, 0, v16
	ds_write_b128 v220, v[24:27]
	ds_read_b128 v[232:235], v221
	v_mov_b64_e32 v[240:241], v[30:31]
	s_waitcnt lgkmcnt(2)
	global_store_dwordx4 v[242:243], v[236:239], off offset:256
	v_max_f32_e32 v17, 0, v17
	v_max_f32_e32 v18, 0, v18
	v_mul_f32_e32 v24, v16, v16
	v_max_f32_e32 v16, v21, v21
	v_max_f32_e32 v16, 0, v16
	v_mul_f32_e32 v21, v17, v17
	v_max_f32_e32 v17, v22, v22
	v_mul_f32_e32 v22, v18, v18
	v_max_f32_e32 v18, v23, v23
	v_max_f32_e32 v20, 0, v20
	v_mul_f32_e32 v16, v16, v16
	v_max_f32_e32 v17, 0, v17
	v_max_f32_e32 v18, 0, v18
	v_max_f32_e32 v19, 0, v19
	v_lshl_add_u64 v[28:29], v[120:121], 0, s[26:27]
	v_mul_f32_e32 v20, v20, v20
	v_mul_f32_e32 v17, v17, v17
	v_mul_f32_e32 v18, v18, v18
	v_mul_f32_e32 v19, v19, v19
	v_cvt_pk_bf16_f32 v16, v20, v16
	v_max_f32_e32 v8, 0, v8
	v_max_f32_e32 v9, 0, v9
	v_max_f32_e32 v10, 0, v10
	v_cvt_pk_bf16_f32 v17, v17, v18
	v_cvt_pk_bf16_f32 v18, v24, v21
	v_cvt_pk_bf16_f32 v19, v22, v19
	ds_write_b128 v220, v[16:19]
	ds_read_b128 v[236:239], v221
	v_mov_b64_e32 v[242:243], v[28:29]
	s_waitcnt lgkmcnt(2)
	global_store_dwordx4 v[240:241], v[232:235], off
	s_nop 1
	v_mul_f32_e32 v16, v8, v8
	v_max_f32_e32 v8, v13, v13
	v_mul_f32_e32 v13, v9, v9
	v_max_f32_e32 v9, v14, v14
	v_mul_f32_e32 v14, v10, v10
	v_max_f32_e32 v10, v15, v15
	v_max_f32_e32 v8, 0, v8
	v_max_f32_e32 v9, 0, v9
	v_max_f32_e32 v10, 0, v10
	v_max_f32_e32 v11, 0, v11
	v_max_f32_e32 v12, 0, v12
	v_mul_f32_e32 v8, v8, v8
	v_mul_f32_e32 v9, v9, v9
	v_mul_f32_e32 v10, v10, v10
	v_mul_f32_e32 v11, v11, v11
	v_mul_f32_e32 v12, v12, v12
	v_cvt_pk_bf16_f32 v8, v12, v8
	v_cvt_pk_bf16_f32 v9, v9, v10
	v_cvt_pk_bf16_f32 v10, v16, v13
	v_cvt_pk_bf16_f32 v11, v14, v11
	v_add_co_u32_e32 v14, vcc, s70, v120
	v_addc_co_u32_e32 v15, vcc, 0, v121, vcc
	v_max_f32_e32 v0, 0, v0
	v_max_f32_e32 v1, 0, v1
	v_max_f32_e32 v2, 0, v2
	ds_write_b128 v220, v[8:11]
	ds_read_b128 v[232:235], v221
	v_mov_b64_e32 v[240:241], v[14:15]
	s_waitcnt lgkmcnt(2)
	global_store_dwordx4 v[242:243], v[236:239], off offset:256
	s_nop 1
	v_mul_f32_e32 v8, v0, v0
	v_max_f32_e32 v0, v5, v5
	v_mul_f32_e32 v5, v1, v1
	v_max_f32_e32 v1, v6, v6
	v_mul_f32_e32 v6, v2, v2
	v_max_f32_e32 v2, v7, v7
	v_max_f32_e32 v0, 0, v0
	v_max_f32_e32 v1, 0, v1
	v_max_f32_e32 v2, 0, v2
	v_max_f32_e32 v3, 0, v3
	v_lshl_add_u64 v[12:13], v[120:121], 0, s[28:29]
	v_max_f32_e32 v4, 0, v4
	v_mul_f32_e32 v0, v0, v0
	v_mul_f32_e32 v1, v1, v1
	v_mul_f32_e32 v2, v2, v2
	v_mul_f32_e32 v3, v3, v3
	s_andn2_b64 vcc, exec, s[38:39]
	s_mov_b64 s[38:39], -1
	v_mul_f32_e32 v4, v4, v4
	v_cvt_pk_bf16_f32 v0, v4, v0
	v_cvt_pk_bf16_f32 v1, v1, v2
	v_cvt_pk_bf16_f32 v2, v8, v5
	v_cvt_pk_bf16_f32 v3, v6, v3
	ds_write_b128 v220, v[0:3]
	ds_read_b128 v[236:239], v221
	v_mov_b64_e32 v[242:243], v[12:13]
	s_waitcnt lgkmcnt(2)
	global_store_dwordx4 v[240:241], v[232:235], off
	s_waitcnt lgkmcnt(0)
	global_store_dwordx4 v[242:243], v[236:239], off offset:256
	s_cbranch_vccnz .LBB0_1084
	s_andn2_b64 vcc, exec, s[10:11]
	s_cbranch_vccnz .LBB0_1083
	s_barrier
	s_branch .LBB0_1083

;     __device__ __forceinline__ void operator()(Acc& acc, const Unit& u, int wr, int wc, int fr, int fq) const {
;     ...
;         const int row0 = u.pm * BM + wr * 64 + fr, col0 = u.pn * BM + wc * 32 + 8 * fq;
;         u32x4 rw[2][4][2]; float ssv[2][4];
; #pragma unroll
;         for (int ai = 0; ai < 2; ++ai)
; #pragma unroll
;             for (int m = 0; m < 4; ++m) { ssv[ai][m] = sumsq[row0 + ai * HALF + m * 16];
; #pragma unroll
;                 for (int bj = 0; bj < 2; ++bj) rw[ai][m][bj] = *(const u32x4*)(baseb + (size_t)(row0 + ai * HALF + m * 16) * D + col0 + bj * HALF); }
;         __builtin_amdgcn_sched_barrier(0);
; #pragma unroll
;         for (int ai = 0; ai < 2; ++ai)
; #pragma unroll
;             for (int m = 0; m < 4; ++m) { const size_t o_ = (size_t)(row0 + ai * HALF + m * 16) * D + col0; const float r2 = 1.0f / (ssv[ai][m] * (1.0f / D) + EPS);
; #pragma unroll
;                 for (int bj = 0; bj < 2; ++bj) { const u32x4 w = rw[ai][m][bj];
;                     const f32x4 h0 = (f32x4){bflo(w.x), bfhi(w.x), bflo(w.y), bfhi(w.y)} + acc[ai][bj][m][0] * r2, h1 = (f32x4){bflo(w.z), bfhi(w.z), bflo(w.w), bfhi(w.w)} + acc[ai][bj][m][1] * r2;
;                     *(f32x4*)(out + o_ + bj * HALF) = h0; *(f32x4*)(out + o_ + bj * HALF + 4) = h1; } }
.LBB0_1182:
	s_lshl_b32 s56, s2, 20
	s_lshl_b32 s57, s45, 10
	s_add_i32 s56, s56, s57
	s_add_u32 s58, s90, s56
	s_addc_u32 s59, s91, 0
	s_lshl_b32 s60, s39, 12
	s_lshl_b32 s61, s40, 2
	s_add_i32 s60, s60, s61
	s_lshr_b32 s61, s39, 4
	s_lshr_b32 s56, s40, 5
	s_add_i32 s61, s61, s56
	s_mul_i32 s61, s61, 0x900
	s_add_i32 s61, s61, 0x20000
	v_mbcnt_lo_u32_b32 v245, -1, 0
	v_mbcnt_hi_u32_b32 v245, -1, v245
	v_lshrrev_b32_e32 v242, 3, v245
	v_lshlrev_b32_e32 v242, 12, v242
	v_and_b32_e32 v244, 7, v245
	v_lshl_or_b32 v242, v244, 4, v242
	v_add_u32_e32 v242, s60, v242
	v_lshrrev_b32_e32 v243, 3, v245
	v_mul_u32_u24_e32 v243, 0x90, v243
	v_lshl_add_u32 v244, v244, 4, v243
	v_add_u32_e32 v244, s61, v244
	v_mul_u32_u24_e32 v243, 0x90, v200
	v_lshl_add_u32 v243, v201, 5, v243
	v_add_u32_e32 v243, s61, v243
	s_lshl_b32 s2, s2, 8
	v_mov_b32_e32 v128, v201
	v_mov_b32_e32 v129, v200
	s_add_i32 s2, s2, s39
	s_nop 0
	v_add_u32_e32 v226, s2, v129
	s_lshl_b32 s2, s45, 8
	s_or_b32 s2, s2, s40
	v_lshl_add_u32 v228, v128, 3, s2
	v_ashrrev_i32_e32 v229, 31, v228
	v_ashrrev_i32_e32 v227, 31, v226
	v_lshl_add_u64 v[128:129], v[228:229], 1, s[6:7]
	v_lshlrev_b64 v[132:133], 11, v[226:227]
	v_add_u32_e32 v230, 16, v226
	v_lshl_add_u64 v[132:133], v[128:129], 0, v[132:133]
	v_ashrrev_i32_e32 v231, 31, v230
	global_load_dwordx4 v[210:213], v[132:133], off
	global_load_dwordx4 v[214:217], v[132:133], off offset:256
	v_lshlrev_b64 v[132:133], 11, v[230:231]
	v_add_u32_e32 v198, 32, v226
	v_lshl_add_u64 v[132:133], v[128:129], 0, v[132:133]
	v_ashrrev_i32_e32 v199, 31, v198
	global_load_dwordx4 v[218:221], v[132:133], off
	global_load_dwordx4 v[222:225], v[132:133], off offset:256
	v_lshlrev_b64 v[132:133], 11, v[198:199]
	v_add_u32_e32 v196, 48, v226
	v_lshl_add_u64 v[132:133], v[128:129], 0, v[132:133]
	v_ashrrev_i32_e32 v197, 31, v196
	global_load_dwordx4 v[172:175], v[132:133], off
	global_load_dwordx4 v[168:171], v[132:133], off offset:256
	v_lshlrev_b64 v[132:133], 11, v[196:197]
	v_add_u32_e32 v194, 0x80, v226
	v_lshl_add_u64 v[132:133], v[128:129], 0, v[132:133]
	v_ashrrev_i32_e32 v195, 31, v194
	global_load_dwordx4 v[164:167], v[132:133], off
	global_load_dwordx4 v[160:163], v[132:133], off offset:256
	v_lshlrev_b64 v[132:133], 11, v[194:195]
	v_add_u32_e32 v192, 0x90, v226
	v_lshl_add_u64 v[132:133], v[128:129], 0, v[132:133]
	v_ashrrev_i32_e32 v193, 31, v192
	global_load_dwordx4 v[156:159], v[132:133], off
	global_load_dwordx4 v[152:155], v[132:133], off offset:256
	v_lshlrev_b64 v[132:133], 11, v[192:193]
	v_add_u32_e32 v190, 0xa0, v226
	v_lshl_add_u64 v[132:133], v[128:129], 0, v[132:133]
	v_ashrrev_i32_e32 v191, 31, v190
	global_load_dwordx4 v[148:151], v[132:133], off
	global_load_dwordx4 v[144:147], v[132:133], off offset:256
	v_lshlrev_b64 v[132:133], 11, v[190:191]
	v_lshl_add_u64 v[130:131], v[226:227], 2, s[0:1]
	v_lshl_add_u64 v[132:133], v[128:129], 0, v[132:133]
	global_load_dwordx4 v[140:143], v[132:133], off
	global_load_dwordx4 v[136:139], v[132:133], off offset:256
	global_load_dword v209, v[130:131], off
	global_load_dword v233, v[130:131], off offset:64
	global_load_dword v236, v[130:131], off offset:128
	global_load_dword v237, v[130:131], off offset:192
	global_load_dword v238, v[130:131], off offset:512
	global_load_dword v239, v[130:131], off offset:576
	global_load_dword v208, v[130:131], off offset:640
	global_load_dword v207, v[130:131], off offset:704
	v_add_u32_e32 v188, 0xb0, v226
	v_ashrrev_i32_e32 v189, 31, v188
	v_lshlrev_b64 v[130:131], 11, v[188:189]
	v_lshl_add_u64 v[128:129], v[128:129], 0, v[130:131]
	global_load_dwordx4 v[132:135], v[128:129], off
	s_nop 0
	global_load_dwordx4 v[128:131], v[128:129], off offset:256
	s_waitcnt vmcnt(0)
	v_fmamk_f32 v209, v209, 0x3a800000, v206
	v_div_scale_f32 v232, s[22:23], v209, v209, 1.0
	v_rcp_f32_e32 v234, v232
	v_div_scale_f32 v235, vcc, 1.0, v209, 1.0
	v_fma_f32 v240, -v232, v234, 1.0
	v_fmac_f32_e32 v234, v240, v234
	v_mul_f32_e32 v240, v235, v234
	v_fma_f32 v241, -v232, v240, v235
	v_fmac_f32_e32 v240, v241, v234
	v_fma_f32 v232, -v232, v240, v235
	v_div_fmas_f32 v232, v232, v234, v240
	v_div_fixup_f32 v232, v232, v209, 1.0
	v_lshlrev_b32_e32 v234, 16, v210
	v_and_b32_e32 v235, 0xffff0000, v210
	v_lshlrev_b32_e32 v210, 16, v211
	v_and_b32_e32 v211, 0xffff0000, v211
	v_pk_fma_f32 v[126:127], v[126:127], v[232:233], v[210:211] op_sel_hi:[1,0,1]
	v_lshlrev_b32_e32 v210, 16, v212
	v_and_b32_e32 v211, 0xffff0000, v212
	v_lshlrev_b32_e32 v212, 16, v213
	v_and_b32_e32 v213, 0xffff0000, v213
	v_pk_fma_f32 v[210:211], v[120:121], v[232:233], v[210:211] op_sel_hi:[1,0,1]
	v_lshlrev_b64 v[120:121], 12, v[226:227]
	v_pk_fma_f32 v[212:213], v[122:123], v[232:233], v[212:213] op_sel_hi:[1,0,1]
	v_lshl_add_u64 v[122:123], s[90:91], 0, v[120:121]
	v_lshlrev_b64 v[120:121], 2, v[228:229]
	v_pk_fma_f32 v[124:125], v[124:125], v[232:233], v[234:235] op_sel_hi:[1,0,1]
	v_lshl_add_u64 v[122:123], v[122:123], 0, v[120:121]
	s_mov_b64 s[62:63], s[58:59]
	s_add_u32 s64, s62, 0x8000
	s_addc_u32 s65, s63, 0
	ds_write_b128 v243, v[124:127]
	ds_write_b128 v243, v[210:213] offset:16
	ds_read_b128 v[246:249], v244
	ds_read_b128 v[250:253], v244 offset:1152
	s_nop 0
	v_lshlrev_b32_e32 v126, 16, v215
	v_and_b32_e32 v127, 0xffff0000, v215
	v_pk_fma_f32 v[118:119], v[118:119], v[232:233], v[126:127] op_sel_hi:[1,0,1]
	v_lshlrev_b32_e32 v126, 16, v217
	v_and_b32_e32 v127, 0xffff0000, v217
	v_pk_fma_f32 v[110:111], v[110:111], v[232:233], v[126:127] op_sel_hi:[1,0,1]
	v_fmamk_f32 v126, v233, 0x3a800000, v206
	v_div_scale_f32 v127, s[22:23], v126, v126, 1.0
	v_rcp_f32_e32 v209, v127
	v_lshlrev_b32_e32 v124, 16, v214
	v_and_b32_e32 v125, 0xffff0000, v214
	v_pk_fma_f32 v[116:117], v[116:117], v[232:233], v[124:125] op_sel_hi:[1,0,1]
	v_lshlrev_b32_e32 v124, 16, v216
	v_and_b32_e32 v125, 0xffff0000, v216
	v_pk_fma_f32 v[108:109], v[108:109], v[232:233], v[124:125] op_sel_hi:[1,0,1]
	s_waitcnt lgkmcnt(0)
;     __device__ __forceinline__ void operator()(Acc& acc, const Unit& u, int wr, int wc, int fr, int fq) const {
;     ...
; #pragma unroll
;         for (int ai = 0; ai < 2; ++ai)
; #pragma unroll
;             for (int m = 0; m < 4; ++m) { const size_t o_ = (size_t)(row0 + ai * HALF + m * 16) * D + col0; const float r2 = 1.0f / (ssv[ai][m] * (1.0f / D) + EPS);
; #pragma unroll
;                 for (int bj = 0; bj < 2; ++bj) { const u32x4 w = rw[ai][m][bj];
;                     const f32x4 h0 = (f32x4){bflo(w.x), bfhi(w.x), bflo(w.y), bfhi(w.y)} + acc[ai][bj][m][0] * r2, h1 = (f32x4){bflo(w.z), bfhi(w.z), bflo(w.w), bfhi(w.w)} + acc[ai][bj][m][1] * r2;
;                     *(f32x4*)(out + o_ + bj * HALF) = h0; *(f32x4*)(out + o_ + bj * HALF + 4) = h1; } }
	global_store_dwordx4 v242, v[246:249], s[62:63]
	global_store_dwordx4 v242, v[250:253], s[64:65]
	ds_write_b128 v243, v[116:119]
	ds_write_b128 v243, v[108:111] offset:16
	ds_read_b128 v[246:249], v244
	ds_read_b128 v[250:253], v244 offset:1152
	s_nop 1
	v_fma_f32 v108, -v127, v209, 1.0
	v_fmac_f32_e32 v209, v108, v209
	v_div_scale_f32 v108, vcc, 1.0, v126, 1.0
	v_mul_f32_e32 v109, v108, v209
	v_fma_f32 v110, -v127, v109, v108
	v_fmac_f32_e32 v109, v110, v209
	v_fma_f32 v108, -v127, v109, v108
	v_div_fmas_f32 v108, v108, v209, v109
	v_div_fixup_f32 v116, v108, v126, 1.0
	v_lshlrev_b32_e32 v108, 16, v218
	v_and_b32_e32 v109, 0xffff0000, v218
	v_pk_fma_f32 v[108:109], v[112:113], v[116:117], v[108:109] op_sel_hi:[1,0,1]
	v_lshlrev_b32_e32 v112, 16, v220
	v_and_b32_e32 v113, 0xffff0000, v220
	v_lshlrev_b32_e32 v110, 16, v219
	v_and_b32_e32 v111, 0xffff0000, v219
	v_pk_fma_f32 v[104:105], v[104:105], v[116:117], v[112:113] op_sel_hi:[1,0,1]
	v_lshlrev_b64 v[112:113], 12, v[230:231]
	v_pk_fma_f32 v[110:111], v[114:115], v[116:117], v[110:111] op_sel_hi:[1,0,1]
	v_lshlrev_b32_e32 v114, 16, v221
	v_and_b32_e32 v115, 0xffff0000, v221
	v_lshl_add_u64 v[112:113], s[90:91], 0, v[112:113]
	v_pk_fma_f32 v[106:107], v[106:107], v[116:117], v[114:115] op_sel_hi:[1,0,1]
	v_lshl_add_u64 v[112:113], v[112:113], 0, v[120:121]
	s_waitcnt lgkmcnt(0)
	global_store_dwordx4 v242, v[246:249], s[62:63] offset:512
	global_store_dwordx4 v242, v[250:253], s[64:65] offset:512
	s_add_u32 s62, s58, 0x10000
	s_addc_u32 s63, s59, 0
	s_add_u32 s64, s62, 0x8000
	s_addc_u32 s65, s63, 0
	ds_write_b128 v243, v[108:111]
	ds_write_b128 v243, v[104:107] offset:16
	ds_read_b128 v[246:249], v244
	ds_read_b128 v[250:253], v244 offset:1152
	s_nop 1
	v_lshlrev_b32_e32 v106, 16, v223
	v_and_b32_e32 v107, 0xffff0000, v223
	v_pk_fma_f32 v[102:103], v[102:103], v[116:117], v[106:107] op_sel_hi:[1,0,1]
	v_lshlrev_b32_e32 v106, 16, v225
	v_and_b32_e32 v107, 0xffff0000, v225
	v_pk_fma_f32 v[94:95], v[94:95], v[116:117], v[106:107] op_sel_hi:[1,0,1]
	v_fmamk_f32 v106, v236, 0x3a800000, v206
	v_div_scale_f32 v107, s[22:23], v106, v106, 1.0
	v_rcp_f32_e32 v108, v107
	v_lshlrev_b32_e32 v104, 16, v222
	v_and_b32_e32 v105, 0xffff0000, v222
	v_pk_fma_f32 v[100:101], v[100:101], v[116:117], v[104:105] op_sel_hi:[1,0,1]
	v_lshlrev_b32_e32 v104, 16, v224
	v_and_b32_e32 v105, 0xffff0000, v224
	v_pk_fma_f32 v[92:93], v[92:93], v[116:117], v[104:105] op_sel_hi:[1,0,1]
	s_waitcnt lgkmcnt(0)
	global_store_dwordx4 v242, v[246:249], s[62:63]
	global_store_dwordx4 v242, v[250:253], s[64:65]
	ds_write_b128 v243, v[100:103]
	ds_write_b128 v243, v[92:95] offset:16
	ds_read_b128 v[246:249], v244
	ds_read_b128 v[250:253], v244 offset:1152
	s_nop 1
	v_fma_f32 v92, -v107, v108, 1.0
	v_fmac_f32_e32 v108, v92, v108
	v_div_scale_f32 v92, vcc, 1.0, v106, 1.0
	v_mul_f32_e32 v93, v92, v108
	v_fma_f32 v94, -v107, v93, v92
	v_fmac_f32_e32 v93, v94, v108
	v_fma_f32 v92, -v107, v93, v92
	v_div_fmas_f32 v92, v92, v108, v93
	v_div_fixup_f32 v100, v92, v106, 1.0
	v_lshlrev_b32_e32 v92, 16, v172
	v_and_b32_e32 v93, 0xffff0000, v172
	v_pk_fma_f32 v[92:93], v[96:97], v[100:101], v[92:93] op_sel_hi:[1,0,1]
	v_lshlrev_b32_e32 v96, 16, v174
	v_and_b32_e32 v97, 0xffff0000, v174
	v_lshlrev_b32_e32 v94, 16, v173
	v_and_b32_e32 v95, 0xffff0000, v173
	v_pk_fma_f32 v[88:89], v[88:89], v[100:101], v[96:97] op_sel_hi:[1,0,1]
	v_lshlrev_b64 v[96:97], 12, v[198:199]
	v_pk_fma_f32 v[94:95], v[98:99], v[100:101], v[94:95] op_sel_hi:[1,0,1]
	v_lshlrev_b32_e32 v98, 16, v175
	v_and_b32_e32 v99, 0xffff0000, v175
	v_lshl_add_u64 v[96:97], s[90:91], 0, v[96:97]
	v_pk_fma_f32 v[90:91], v[90:91], v[100:101], v[98:99] op_sel_hi:[1,0,1]
	v_lshl_add_u64 v[96:97], v[96:97], 0, v[120:121]
	s_waitcnt lgkmcnt(0)
	global_store_dwordx4 v242, v[246:249], s[62:63] offset:512
	global_store_dwordx4 v242, v[250:253], s[64:65] offset:512
	s_add_u32 s62, s58, 0x20000
	s_addc_u32 s63, s59, 0
	s_add_u32 s64, s62, 0x8000
	s_addc_u32 s65, s63, 0
	ds_write_b128 v243, v[92:95]
	ds_write_b128 v243, v[88:91] offset:16
	ds_read_b128 v[246:249], v244
	ds_read_b128 v[250:253], v244 offset:1152
	s_nop 1
	v_lshlrev_b32_e32 v90, 16, v169
	v_and_b32_e32 v91, 0xffff0000, v169
	v_pk_fma_f32 v[86:87], v[86:87], v[100:101], v[90:91] op_sel_hi:[1,0,1]
	v_lshlrev_b32_e32 v90, 16, v171
	v_and_b32_e32 v91, 0xffff0000, v171
	v_pk_fma_f32 v[78:79], v[78:79], v[100:101], v[90:91] op_sel_hi:[1,0,1]
	v_fmamk_f32 v90, v237, 0x3a800000, v206
	v_div_scale_f32 v91, s[22:23], v90, v90, 1.0
	v_rcp_f32_e32 v92, v91
	v_lshlrev_b32_e32 v88, 16, v168
	v_and_b32_e32 v89, 0xffff0000, v168
	v_pk_fma_f32 v[84:85], v[84:85], v[100:101], v[88:89] op_sel_hi:[1,0,1]
	v_lshlrev_b32_e32 v88, 16, v170
	v_and_b32_e32 v89, 0xffff0000, v170
	v_pk_fma_f32 v[76:77], v[76:77], v[100:101], v[88:89] op_sel_hi:[1,0,1]
	s_waitcnt lgkmcnt(0)
	global_store_dwordx4 v242, v[246:249], s[62:63]
	global_store_dwordx4 v242, v[250:253], s[64:65]
	ds_write_b128 v243, v[84:87]
	ds_write_b128 v243, v[76:79] offset:16
	ds_read_b128 v[246:249], v244
	ds_read_b128 v[250:253], v244 offset:1152
	s_nop 1
	v_fma_f32 v76, -v91, v92, 1.0
	v_fmac_f32_e32 v92, v76, v92
	v_div_scale_f32 v76, vcc, 1.0, v90, 1.0
	v_mul_f32_e32 v77, v76, v92
	v_fma_f32 v78, -v91, v77, v76
	v_fmac_f32_e32 v77, v78, v92
	v_fma_f32 v76, -v91, v77, v76
	v_div_fmas_f32 v76, v76, v92, v77
	v_div_fixup_f32 v84, v76, v90, 1.0
	v_lshlrev_b32_e32 v76, 16, v164
	v_and_b32_e32 v77, 0xffff0000, v164
	v_pk_fma_f32 v[76:77], v[80:81], v[84:85], v[76:77] op_sel_hi:[1,0,1]
	v_lshlrev_b32_e32 v80, 16, v166
	v_and_b32_e32 v81, 0xffff0000, v166
	v_lshlrev_b32_e32 v78, 16, v165
	v_and_b32_e32 v79, 0xffff0000, v165
	v_pk_fma_f32 v[72:73], v[72:73], v[84:85], v[80:81] op_sel_hi:[1,0,1]
	v_lshlrev_b64 v[80:81], 12, v[196:197]
	v_pk_fma_f32 v[78:79], v[82:83], v[84:85], v[78:79] op_sel_hi:[1,0,1]
	v_lshlrev_b32_e32 v82, 16, v167
	v_and_b32_e32 v83, 0xffff0000, v167
	v_lshl_add_u64 v[80:81], s[90:91], 0, v[80:81]
	v_pk_fma_f32 v[74:75], v[74:75], v[84:85], v[82:83] op_sel_hi:[1,0,1]
	v_lshl_add_u64 v[80:81], v[80:81], 0, v[120:121]
	s_waitcnt lgkmcnt(0)
;     __device__ __forceinline__ void operator()(Acc& acc, const Unit& u, int wr, int wc, int fr, int fq) const {
;     ...
; #pragma unroll
;         for (int ai = 0; ai < 2; ++ai)
; #pragma unroll
;             for (int m = 0; m < 4; ++m) { const size_t o_ = (size_t)(row0 + ai * HALF + m * 16) * D + col0; const float r2 = 1.0f / (ssv[ai][m] * (1.0f / D) + EPS);
; #pragma unroll
;                 for (int bj = 0; bj < 2; ++bj) { const u32x4 w = rw[ai][m][bj];
;                     const f32x4 h0 = (f32x4){bflo(w.x), bfhi(w.x), bflo(w.y), bfhi(w.y)} + acc[ai][bj][m][0] * r2, h1 = (f32x4){bflo(w.z), bfhi(w.z), bflo(w.w), bfhi(w.w)} + acc[ai][bj][m][1] * r2;
;                     *(f32x4*)(out + o_ + bj * HALF) = h0; *(f32x4*)(out + o_ + bj * HALF + 4) = h1; } }
	global_store_dwordx4 v242, v[246:249], s[62:63] offset:512
	global_store_dwordx4 v242, v[250:253], s[64:65] offset:512
	s_add_u32 s62, s58, 0x30000
	s_addc_u32 s63, s59, 0
	s_add_u32 s64, s62, 0x8000
	s_addc_u32 s65, s63, 0
	ds_write_b128 v243, v[76:79]
	ds_write_b128 v243, v[72:75] offset:16
	ds_read_b128 v[246:249], v244
	ds_read_b128 v[250:253], v244 offset:1152
	s_nop 1
	v_lshlrev_b32_e32 v74, 16, v161
	v_and_b32_e32 v75, 0xffff0000, v161
	v_pk_fma_f32 v[70:71], v[70:71], v[84:85], v[74:75] op_sel_hi:[1,0,1]
	v_lshlrev_b32_e32 v74, 16, v163
	v_and_b32_e32 v75, 0xffff0000, v163
	v_pk_fma_f32 v[66:67], v[66:67], v[84:85], v[74:75] op_sel_hi:[1,0,1]
	v_fmamk_f32 v74, v238, 0x3a800000, v206
	v_div_scale_f32 v75, s[22:23], v74, v74, 1.0
	v_rcp_f32_e32 v76, v75
	v_lshlrev_b32_e32 v72, 16, v160
	v_and_b32_e32 v73, 0xffff0000, v160
	v_pk_fma_f32 v[68:69], v[68:69], v[84:85], v[72:73] op_sel_hi:[1,0,1]
	v_lshlrev_b32_e32 v72, 16, v162
	v_and_b32_e32 v73, 0xffff0000, v162
	v_pk_fma_f32 v[64:65], v[64:65], v[84:85], v[72:73] op_sel_hi:[1,0,1]
	s_waitcnt lgkmcnt(0)
	global_store_dwordx4 v242, v[246:249], s[62:63]
	global_store_dwordx4 v242, v[250:253], s[64:65]
	ds_write_b128 v243, v[68:71]
	ds_write_b128 v243, v[64:67] offset:16
	ds_read_b128 v[246:249], v244
	ds_read_b128 v[250:253], v244 offset:1152
	s_nop 0
	v_lshlrev_b32_e32 v68, 16, v157
	v_fma_f32 v64, -v75, v76, 1.0
	v_fmac_f32_e32 v76, v64, v76
	v_div_scale_f32 v64, vcc, 1.0, v74, 1.0
	v_mul_f32_e32 v65, v64, v76
	v_fma_f32 v66, -v75, v65, v64
	v_fmac_f32_e32 v65, v66, v76
	v_fma_f32 v64, -v75, v65, v64
	v_div_fmas_f32 v64, v64, v76, v65
	v_div_fixup_f32 v64, v64, v74, 1.0
	v_lshlrev_b32_e32 v66, 16, v156
	v_and_b32_e32 v67, 0xffff0000, v156
	v_pk_fma_f32 v[60:61], v[60:61], v[64:65], v[66:67] op_sel_hi:[1,0,1]
	v_lshlrev_b32_e32 v66, 16, v158
	v_and_b32_e32 v67, 0xffff0000, v158
	v_and_b32_e32 v69, 0xffff0000, v157
	v_pk_fma_f32 v[56:57], v[56:57], v[64:65], v[66:67] op_sel_hi:[1,0,1]
	v_lshlrev_b64 v[66:67], 12, v[194:195]
	v_pk_fma_f32 v[62:63], v[62:63], v[64:65], v[68:69] op_sel_hi:[1,0,1]
	v_lshlrev_b32_e32 v68, 16, v159
	v_and_b32_e32 v69, 0xffff0000, v159
	v_lshl_add_u64 v[66:67], s[90:91], 0, v[66:67]
	v_pk_fma_f32 v[58:59], v[58:59], v[64:65], v[68:69] op_sel_hi:[1,0,1]
	v_lshl_add_u64 v[66:67], v[66:67], 0, v[120:121]
	s_waitcnt lgkmcnt(0)
	global_store_dwordx4 v242, v[246:249], s[62:63] offset:512
	global_store_dwordx4 v242, v[250:253], s[64:65] offset:512
	s_add_u32 s62, s58, 0x80000
	s_addc_u32 s63, s59, 0
	s_add_u32 s64, s62, 0x8000
	s_addc_u32 s65, s63, 0
	ds_write_b128 v243, v[60:63]
	ds_write_b128 v243, v[56:59] offset:16
	ds_read_b128 v[246:249], v244
	ds_read_b128 v[250:253], v244 offset:1152
	s_nop 1
	v_lshlrev_b32_e32 v58, 16, v153
	v_and_b32_e32 v59, 0xffff0000, v153
	v_pk_fma_f32 v[54:55], v[54:55], v[64:65], v[58:59] op_sel_hi:[1,0,1]
	v_lshlrev_b32_e32 v58, 16, v155
	v_and_b32_e32 v59, 0xffff0000, v155
	v_pk_fma_f32 v[46:47], v[46:47], v[64:65], v[58:59] op_sel_hi:[1,0,1]
	v_fmamk_f32 v58, v239, 0x3a800000, v206
	v_div_scale_f32 v59, s[22:23], v58, v58, 1.0
	v_rcp_f32_e32 v60, v59
	v_lshlrev_b32_e32 v56, 16, v152
	v_and_b32_e32 v57, 0xffff0000, v152
	v_pk_fma_f32 v[52:53], v[52:53], v[64:65], v[56:57] op_sel_hi:[1,0,1]
	v_lshlrev_b32_e32 v56, 16, v154
	v_and_b32_e32 v57, 0xffff0000, v154
	v_pk_fma_f32 v[44:45], v[44:45], v[64:65], v[56:57] op_sel_hi:[1,0,1]
	s_waitcnt lgkmcnt(0)
	global_store_dwordx4 v242, v[246:249], s[62:63]
	global_store_dwordx4 v242, v[250:253], s[64:65]
	ds_write_b128 v243, v[52:55]
	ds_write_b128 v243, v[44:47] offset:16
	ds_read_b128 v[246:249], v244
	ds_read_b128 v[250:253], v244 offset:1152
	s_nop 1
	v_fma_f32 v44, -v59, v60, 1.0
	v_fmac_f32_e32 v60, v44, v60
	v_div_scale_f32 v44, vcc, 1.0, v58, 1.0
	v_mul_f32_e32 v45, v44, v60
	v_fma_f32 v46, -v59, v45, v44
	v_fmac_f32_e32 v45, v46, v60
	v_fma_f32 v44, -v59, v45, v44
	v_div_fmas_f32 v44, v44, v60, v45
	v_div_fixup_f32 v52, v44, v58, 1.0
	v_lshlrev_b32_e32 v44, 16, v148
	v_and_b32_e32 v45, 0xffff0000, v148
	v_pk_fma_f32 v[44:45], v[48:49], v[52:53], v[44:45] op_sel_hi:[1,0,1]
	v_lshlrev_b32_e32 v48, 16, v150
	v_and_b32_e32 v49, 0xffff0000, v150
	v_lshlrev_b32_e32 v46, 16, v149
	v_and_b32_e32 v47, 0xffff0000, v149
	v_pk_fma_f32 v[40:41], v[40:41], v[52:53], v[48:49] op_sel_hi:[1,0,1]
	v_lshlrev_b64 v[48:49], 12, v[192:193]
	v_pk_fma_f32 v[46:47], v[50:51], v[52:53], v[46:47] op_sel_hi:[1,0,1]
	v_lshlrev_b32_e32 v50, 16, v151
	v_and_b32_e32 v51, 0xffff0000, v151
	v_lshl_add_u64 v[48:49], s[90:91], 0, v[48:49]
	v_pk_fma_f32 v[42:43], v[42:43], v[52:53], v[50:51] op_sel_hi:[1,0,1]
	v_lshl_add_u64 v[48:49], v[48:49], 0, v[120:121]
	s_waitcnt lgkmcnt(0)
	global_store_dwordx4 v242, v[246:249], s[62:63] offset:512
	global_store_dwordx4 v242, v[250:253], s[64:65] offset:512
	s_add_u32 s62, s58, 0x90000
	s_addc_u32 s63, s59, 0
	s_add_u32 s64, s62, 0x8000
	s_addc_u32 s65, s63, 0
	ds_write_b128 v243, v[44:47]
	ds_write_b128 v243, v[40:43] offset:16
	ds_read_b128 v[246:249], v244
	ds_read_b128 v[250:253], v244 offset:1152
	s_nop 1
	v_lshlrev_b32_e32 v42, 16, v145
	v_and_b32_e32 v43, 0xffff0000, v145
	v_pk_fma_f32 v[38:39], v[38:39], v[52:53], v[42:43] op_sel_hi:[1,0,1]
	v_lshlrev_b32_e32 v42, 16, v147
	v_and_b32_e32 v43, 0xffff0000, v147
	v_pk_fma_f32 v[30:31], v[30:31], v[52:53], v[42:43] op_sel_hi:[1,0,1]
	v_fmamk_f32 v42, v208, 0x3a800000, v206
	v_div_scale_f32 v43, s[22:23], v42, v42, 1.0
	v_rcp_f32_e32 v44, v43
	v_lshlrev_b32_e32 v40, 16, v144
	v_and_b32_e32 v41, 0xffff0000, v144
	v_pk_fma_f32 v[36:37], v[36:37], v[52:53], v[40:41] op_sel_hi:[1,0,1]
	v_lshlrev_b32_e32 v40, 16, v146
	v_and_b32_e32 v41, 0xffff0000, v146
	v_pk_fma_f32 v[28:29], v[28:29], v[52:53], v[40:41] op_sel_hi:[1,0,1]
	s_waitcnt lgkmcnt(0)
;     __device__ __forceinline__ void operator()(Acc& acc, const Unit& u, int wr, int wc, int fr, int fq) const {
;     ...
; #pragma unroll
;         for (int ai = 0; ai < 2; ++ai)
; #pragma unroll
;             for (int m = 0; m < 4; ++m) { const size_t o_ = (size_t)(row0 + ai * HALF + m * 16) * D + col0; const float r2 = 1.0f / (ssv[ai][m] * (1.0f / D) + EPS);
; #pragma unroll
;                 for (int bj = 0; bj < 2; ++bj) { const u32x4 w = rw[ai][m][bj];
;                     const f32x4 h0 = (f32x4){bflo(w.x), bfhi(w.x), bflo(w.y), bfhi(w.y)} + acc[ai][bj][m][0] * r2, h1 = (f32x4){bflo(w.z), bfhi(w.z), bflo(w.w), bfhi(w.w)} + acc[ai][bj][m][1] * r2;
;                     *(f32x4*)(out + o_ + bj * HALF) = h0; *(f32x4*)(out + o_ + bj * HALF + 4) = h1; } }
	global_store_dwordx4 v242, v[246:249], s[62:63]
	global_store_dwordx4 v242, v[250:253], s[64:65]
	ds_write_b128 v243, v[36:39]
	ds_write_b128 v243, v[28:31] offset:16
	ds_read_b128 v[246:249], v244
	ds_read_b128 v[250:253], v244 offset:1152
	s_nop 1
	v_fma_f32 v28, -v43, v44, 1.0
	v_fmac_f32_e32 v44, v28, v44
	v_div_scale_f32 v28, vcc, 1.0, v42, 1.0
	v_mul_f32_e32 v29, v28, v44
	v_fma_f32 v30, -v43, v29, v28
	v_fmac_f32_e32 v29, v30, v44
	v_fma_f32 v28, -v43, v29, v28
	v_div_fmas_f32 v28, v28, v44, v29
	v_div_fixup_f32 v36, v28, v42, 1.0
	v_lshlrev_b32_e32 v28, 16, v140
	v_and_b32_e32 v29, 0xffff0000, v140
	v_pk_fma_f32 v[28:29], v[32:33], v[36:37], v[28:29] op_sel_hi:[1,0,1]
	v_lshlrev_b32_e32 v32, 16, v142
	v_and_b32_e32 v33, 0xffff0000, v142
	v_lshlrev_b32_e32 v30, 16, v141
	v_and_b32_e32 v31, 0xffff0000, v141
	v_pk_fma_f32 v[24:25], v[24:25], v[36:37], v[32:33] op_sel_hi:[1,0,1]
	v_lshlrev_b64 v[32:33], 12, v[190:191]
	v_pk_fma_f32 v[30:31], v[34:35], v[36:37], v[30:31] op_sel_hi:[1,0,1]
	v_lshlrev_b32_e32 v34, 16, v143
	v_and_b32_e32 v35, 0xffff0000, v143
	v_lshl_add_u64 v[32:33], s[90:91], 0, v[32:33]
	v_pk_fma_f32 v[26:27], v[26:27], v[36:37], v[34:35] op_sel_hi:[1,0,1]
	v_lshl_add_u64 v[32:33], v[32:33], 0, v[120:121]
	s_waitcnt lgkmcnt(0)
	global_store_dwordx4 v242, v[246:249], s[62:63] offset:512
	global_store_dwordx4 v242, v[250:253], s[64:65] offset:512
	s_add_u32 s62, s58, 0xa0000
	s_addc_u32 s63, s59, 0
	s_add_u32 s64, s62, 0x8000
	s_addc_u32 s65, s63, 0
	ds_write_b128 v243, v[28:31]
	ds_write_b128 v243, v[24:27] offset:16
	ds_read_b128 v[246:249], v244
	ds_read_b128 v[250:253], v244 offset:1152
	s_nop 1
	v_lshlrev_b32_e32 v26, 16, v137
	v_and_b32_e32 v27, 0xffff0000, v137
	v_pk_fma_f32 v[22:23], v[22:23], v[36:37], v[26:27] op_sel_hi:[1,0,1]
	v_lshlrev_b32_e32 v26, 16, v139
	v_and_b32_e32 v27, 0xffff0000, v139
	v_pk_fma_f32 v[14:15], v[14:15], v[36:37], v[26:27] op_sel_hi:[1,0,1]
	v_fmamk_f32 v26, v207, 0x3a800000, v206
	v_div_scale_f32 v27, s[22:23], v26, v26, 1.0
	v_rcp_f32_e32 v28, v27
	v_lshlrev_b32_e32 v24, 16, v136
	v_and_b32_e32 v25, 0xffff0000, v136
	v_pk_fma_f32 v[20:21], v[20:21], v[36:37], v[24:25] op_sel_hi:[1,0,1]
	v_lshlrev_b32_e32 v24, 16, v138
	v_and_b32_e32 v25, 0xffff0000, v138
	v_pk_fma_f32 v[12:13], v[12:13], v[36:37], v[24:25] op_sel_hi:[1,0,1]
	s_waitcnt lgkmcnt(0)
	global_store_dwordx4 v242, v[246:249], s[62:63]
	global_store_dwordx4 v242, v[250:253], s[64:65]
	ds_write_b128 v243, v[20:23]
	ds_write_b128 v243, v[12:15] offset:16
	ds_read_b128 v[246:249], v244
	ds_read_b128 v[250:253], v244 offset:1152
	s_nop 1
	v_fma_f32 v12, -v27, v28, 1.0
	v_fmac_f32_e32 v28, v12, v28
	v_div_scale_f32 v12, vcc, 1.0, v26, 1.0
	v_mul_f32_e32 v13, v12, v28
	v_fma_f32 v14, -v27, v13, v12
	v_fmac_f32_e32 v13, v14, v28
	v_fma_f32 v12, -v27, v13, v12
	v_div_fmas_f32 v12, v12, v28, v13
	v_div_fixup_f32 v20, v12, v26, 1.0
	v_lshlrev_b32_e32 v12, 16, v132
	v_and_b32_e32 v13, 0xffff0000, v132
	v_pk_fma_f32 v[12:13], v[16:17], v[20:21], v[12:13] op_sel_hi:[1,0,1]
	v_lshlrev_b32_e32 v16, 16, v134
	v_and_b32_e32 v17, 0xffff0000, v134
	v_lshlrev_b32_e32 v14, 16, v133
	v_and_b32_e32 v15, 0xffff0000, v133
	v_pk_fma_f32 v[8:9], v[8:9], v[20:21], v[16:17] op_sel_hi:[1,0,1]
	v_lshlrev_b64 v[16:17], 12, v[188:189]
	v_pk_fma_f32 v[14:15], v[18:19], v[20:21], v[14:15] op_sel_hi:[1,0,1]
	v_lshlrev_b32_e32 v18, 16, v135
	v_and_b32_e32 v19, 0xffff0000, v135
	v_lshl_add_u64 v[16:17], s[90:91], 0, v[16:17]
	v_pk_fma_f32 v[10:11], v[10:11], v[20:21], v[18:19] op_sel_hi:[1,0,1]
	v_lshl_add_u64 v[16:17], v[16:17], 0, v[120:121]
	s_waitcnt lgkmcnt(0)
	global_store_dwordx4 v242, v[246:249], s[62:63] offset:512
	global_store_dwordx4 v242, v[250:253], s[64:65] offset:512
	s_add_u32 s62, s58, 0xb0000
	s_addc_u32 s63, s59, 0
	s_add_u32 s64, s62, 0x8000
	s_addc_u32 s65, s63, 0
	ds_write_b128 v243, v[12:15]
	ds_write_b128 v243, v[8:11] offset:16
	ds_read_b128 v[246:249], v244
	ds_read_b128 v[250:253], v244 offset:1152
	s_andn2_b64 vcc, exec, s[18:19]
	s_mov_b64 s[18:19], -1
	v_lshlrev_b32_e32 v8, 16, v128
	v_and_b32_e32 v9, 0xffff0000, v128
	v_lshlrev_b32_e32 v10, 16, v129
	v_and_b32_e32 v11, 0xffff0000, v129
	v_pk_fma_f32 v[6:7], v[6:7], v[20:21], v[10:11] op_sel_hi:[1,0,1]
	v_pk_fma_f32 v[4:5], v[4:5], v[20:21], v[8:9] op_sel_hi:[1,0,1]
	v_lshlrev_b32_e32 v8, 16, v130
	v_and_b32_e32 v9, 0xffff0000, v130
	v_lshlrev_b32_e32 v10, 16, v131
	v_and_b32_e32 v11, 0xffff0000, v131
	v_pk_fma_f32 v[2:3], v[2:3], v[20:21], v[10:11] op_sel_hi:[1,0,1]
	v_pk_fma_f32 v[0:1], v[0:1], v[20:21], v[8:9] op_sel_hi:[1,0,1]
	s_waitcnt lgkmcnt(0)
	global_store_dwordx4 v242, v[246:249], s[62:63]
	global_store_dwordx4 v242, v[250:253], s[64:65]
	ds_write_b128 v243, v[4:7]
	ds_write_b128 v243, v[0:3] offset:16
	ds_read_b128 v[246:249], v244
	ds_read_b128 v[250:253], v244 offset:1152
	s_waitcnt lgkmcnt(0)
	global_store_dwordx4 v242, v[246:249], s[62:63] offset:512
	global_store_dwordx4 v242, v[250:253], s[64:65] offset:512
	s_cbranch_vccnz .LBB0_1175
	s_andn2_b64 vcc, exec, s[4:5]
	s_cbranch_vccnz .LBB0_1174
	s_barrier
	s_branch .LBB0_1174
